# one static s_setprio 1 for the older half (waves 0-3) at kernel entry, no other setprio; on top of the split-barrier version
# speedup vs baseline: 1.0026x; 1.0026x over previous
.Lgc_e0:
	s_or_b64 exec, exec, s[4:5]
	v_readfirstlane_b32 s4, v0
	s_lshr_b32 s4, s4, 6
	s_cmp_lt_u32 s4, 4
	s_cbranch_scc0 .Lprio_skip
	s_setprio 1
.Lprio_skip:
	s_mov_b32 s87, s2
	s_load_dwordx2 s[2:3], s[0:1], 0xe0
	v_cmp_gt_u32_e32 vcc, 8, v0
	s_waitcnt lgkmcnt(0)
	v_writelane_b32 v255, s2, 0
	s_nop 1
	v_writelane_b32 v255, s3, 1
	s_and_saveexec_b64 s[4:5], vcc
	v_lshl_add_u32 v1, v0, 2, 0
	v_add_u32_e32 v1, 0x20000, v1
	v_mov_b32_e32 v2, 0
	ds_write_b32 v1, v2
	s_or_b64 exec, exec, s[4:5]
	s_load_dwordx2 s[2:3], s[0:1], 0xe0
	s_waitcnt lgkmcnt(0)
	s_barrier
	s_sub_i32 s2, s3, s2
	s_cmp_gt_i32 s2, 1
	s_cbranch_scc1 .LBB0_4
	s_mov_b32 s90, 0
	v_cmp_eq_u32_e64 s[4:5], 0, v0
	s_cbranch_execz .LBB0_5
	s_branch .LBB0_9
